# fast body: step barrier moved above the last two PV MFMAs so they overlap the next step's K/P fragment reads
# baseline (speedup 1.0000x reference)
; #define DMAWAIT() asm volatile("s_waitcnt vmcnt(0)" ::: "memory")
; #define SMX_FIN(pbuf) do { _Pragma("unroll") for (int r = 0; r < 16; ++r) l_reg += S[r]; \
;     PK4S(0, po0); PK4S(8, po1); \
;     *(bf16x8*)(pw + (pbuf) * 16384) = po0; *(bf16x8*)(pw + (pbuf) * 16384 + 16) = po1; } while (0)
; #define VRD(D0, X) do { X##0 = tr_read<v_rd_off(D0, 0, 0)>(vb); X##1 = tr_read<v_rd_off(D0, 0, 1)>(vb); X##2 = tr_read<v_rd_off(D0, 1, 0)>(vb); X##3 = tr_read<v_rd_off(D0, 1, 1)>(vb); \
;     X##4 = tr_read<v_rd_off(D0, 2, 0)>(vb); X##5 = tr_read<v_rd_off(D0, 2, 1)>(vb); X##6 = tr_read<v_rd_off(D0, 3, 0)>(vb); X##7 = tr_read<v_rd_off(D0, 3, 1)>(vb); } while (0)
; #define LWAIT() do { asm volatile("s_waitcnt lgkmcnt(0)" ::: "memory"); SBAR(); } while (0)
; #define VMMP(D0, X) do { if (!(PROBE & 8)) VMM(D0, X); } while (0)
; #define SMXP(c) do { if (!(PROBE & 2)) { if (more) SMX_CH(c); } } while (0)
; template <int PROBE, int MODE>
; DI void dattn_body(const u16* __restrict__ Qb, const u16* __restrict__ Kh, const u16* __restrict__ Vh, u16* __restrict__ Ob, const u16* __restrict__ O1, float lam, const float* __restrict__ subg, int seq, int q0, float kmax2, char* lds) {
;     ...
;     LWAIT(); VRD(1, vc); VMMP(0, va); SMXP(0);
;     LWAIT(); VRD(2, va); VMMP(1, vc); SMXP(1);
;     LWAIT(); VRD(3, vc); VMMP(2, va); SMXP(2);
;     LWAIT(); VMMP(3, vc); SMXP(3);
;     if (!(PROBE & 2)) { if (more) SMX_FIN((j + 1) & 1); }
;     DMAWAIT();
;     __syncthreads();
.Lfast0_k_done:
	s_waitcnt lgkmcnt(6)
	v_mfma_f32_32x32x16_bf16 v[0:15], v[114:117], v[234:237], v[0:15]
	ds_read_b64_tr_b16 v[138:139], v216 offset:0x200
	ds_read_b64_tr_b16 v[140:141], v216 offset:0xa00
	s_waitcnt lgkmcnt(6)
	v_mfma_f32_32x32x16_bf16 v[0:15], v[130:133], v[238:241], v[0:15]
	ds_read_b64_tr_b16 v[142:143], v216 offset:0x1200
	ds_read_b64_tr_b16 v[144:145], v216 offset:0x1a00
	s_nop 1
	v_fma_f32 v118, v64, s12, v160
	v_fma_f32 v119, v65, s12, v160
	v_fma_f32 v120, v66, s12, v160
	v_fma_f32 v121, v67, s12, v160
	s_waitcnt lgkmcnt(6)
	v_mfma_f32_32x32x16_bf16 v[0:15], v[162:165], v[242:245], v[0:15]
	ds_read_b64_tr_b16 v[134:135], v233 offset:0x2200
	ds_read_b64_tr_b16 v[136:137], v233 offset:0x2a00
	v_fma_f32 v122, v68, s12, v160
	v_fma_f32 v123, v69, s12, v160
	v_exp_f32_e32 v118, v118
	v_exp_f32_e32 v119, v119
	s_waitcnt lgkmcnt(6)
	v_mfma_f32_32x32x16_bf16 v[0:15], v[166:169], v[246:249], v[0:15]
	ds_read_b64_tr_b16 v[126:127], v233 offset:0x3200
	ds_read_b64_tr_b16 v[128:129], v233 offset:0x3a00
	v_fma_f32 v124, v70, s12, v160
	v_fma_f32 v125, v71, s12, v160
	v_exp_f32_e32 v120, v120
	v_exp_f32_e32 v121, v121
	s_waitcnt lgkmcnt(6)
	v_mfma_f32_32x32x16_bf16 v[16:31], v[114:117], v[138:141], v[16:31]
	ds_read_b64_tr_b16 v[146:147], v216 offset:0x400
	ds_read_b64_tr_b16 v[148:149], v216 offset:0xc00
	v_exp_f32_e32 v122, v122
	v_exp_f32_e32 v123, v123
	v_add_f32_e32 v209, v118, v209
	v_add_f32_e32 v209, v119, v209
	s_waitcnt lgkmcnt(6)
	v_mfma_f32_32x32x16_bf16 v[16:31], v[130:133], v[142:145], v[16:31]
	ds_read_b64_tr_b16 v[142:143], v216 offset:0x1400
	ds_read_b64_tr_b16 v[144:145], v216 offset:0x1c00
	v_exp_f32_e32 v124, v124
	v_exp_f32_e32 v125, v125
	v_add_f32_e32 v209, v120, v209
	v_add_f32_e32 v209, v121, v209
	v_fma_f32 v244, v72, s12, v160
	v_fma_f32 v245, v73, s12, v160
	s_waitcnt lgkmcnt(6)
	v_mfma_f32_32x32x16_bf16 v[16:31], v[162:165], v[134:137], v[16:31]
	ds_read_b64_tr_b16 v[138:139], v233 offset:0x2400
	ds_read_b64_tr_b16 v[140:141], v233 offset:0x2c00
	v_fma_f32 v246, v74, s12, v160
	v_fma_f32 v247, v75, s12, v160
	v_add_f32_e32 v209, v122, v209
	v_add_f32_e32 v209, v123, v209
	s_waitcnt lgkmcnt(6)
	v_mfma_f32_32x32x16_bf16 v[16:31], v[166:169], v[126:129], v[16:31]
	ds_read_b64_tr_b16 v[64:65], v233 offset:0x3400
	ds_read_b64_tr_b16 v[66:67], v233 offset:0x3c00
	v_fma_f32 v76, v76, s12, v160
	v_fma_f32 v77, v77, s12, v160
	v_fma_f32 v78, v78, s12, v160
	v_fma_f32 v79, v79, s12, v160
	s_waitcnt lgkmcnt(6)
	v_mfma_f32_32x32x16_bf16 v[32:47], v[114:117], v[146:149], v[32:47]
	v_exp_f32_e32 v244, v244
	v_exp_f32_e32 v245, v245
	v_add_f32_e32 v209, v124, v209
	v_add_f32_e32 v209, v125, v209
	s_waitcnt lgkmcnt(4)
	v_mfma_f32_32x32x16_bf16 v[32:47], v[130:133], v[142:145], v[32:47]
	ds_read_b64_tr_b16 v[142:143], v216 offset:0x600
	ds_read_b64_tr_b16 v[144:145], v216 offset:0xe00
	ds_read_b64_tr_b16 v[126:127], v216 offset:0x1600
	ds_read_b64_tr_b16 v[128:129], v216 offset:0x1e00
	v_exp_f32_e32 v246, v246
	v_exp_f32_e32 v247, v247
	s_waitcnt lgkmcnt(6)
	v_mfma_f32_32x32x16_bf16 v[32:47], v[162:165], v[138:141], v[32:47]
	ds_read_b64_tr_b16 v[134:135], v233 offset:0x2600
	ds_read_b64_tr_b16 v[136:137], v233 offset:0x2e00
	v_exp_f32_e32 v76, v76
	v_exp_f32_e32 v77, v77
	v_add_f32_e32 v209, v244, v209
	v_add_f32_e32 v209, v245, v209
	s_waitcnt lgkmcnt(6)
	v_mfma_f32_32x32x16_bf16 v[32:47], v[166:169], v[64:67], v[32:47]
	ds_read_b64_tr_b16 v[68:69], v233 offset:0x3600
	ds_read_b64_tr_b16 v[70:71], v233 offset:0x3e00
	v_exp_f32_e32 v78, v78
	v_exp_f32_e32 v79, v79
	v_add_f32_e32 v209, v246, v209
	v_add_f32_e32 v209, v247, v209
	s_waitcnt lgkmcnt(6)
	v_mfma_f32_32x32x16_bf16 v[48:63], v[114:117], v[142:145], v[48:63]
	v_add_u32_e32 v64, s19, v211
	v_add_f32_e32 v209, v76, v209
	v_add_f32_e32 v209, v77, v209
	v_cvt_pk_bf16_f32 v114, v118, v119
	v_cvt_pk_bf16_f32 v115, v120, v121
	v_cvt_pk_bf16_f32 v116, v122, v123
	v_cvt_pk_bf16_f32 v117, v124, v125
	s_waitcnt lgkmcnt(4)
	v_mfma_f32_32x32x16_bf16 v[48:63], v[130:133], v[126:129], v[48:63]
	v_add_f32_e32 v209, v78, v209
	v_add_f32_e32 v209, v79, v209
	v_permlane32_swap_b32_e32 v114, v116
	v_permlane32_swap_b32_e32 v115, v117
	v_cvt_pk_bf16_f32 v130, v244, v245
	v_cvt_pk_bf16_f32 v131, v246, v247
	v_cvt_pk_bf16_f32 v132, v76, v77
	v_cvt_pk_bf16_f32 v133, v78, v79
	ds_write_b128 v64, v[114:117]
	s_nop 0
	v_permlane32_swap_b32_e32 v130, v132
	v_permlane32_swap_b32_e32 v131, v133
	ds_write_b128 v64, v[130:133] offset:16
	s_add_i32 s55, s55, 1
	s_add_i32 s18, s18, 64
	s_add_i32 s54, s54, 0x8000
	s_cmp_eq_u32 s83, s55
	s_waitcnt vmcnt(0) lgkmcnt(0)
	s_barrier
	v_mfma_f32_32x32x16_bf16 v[48:63], v[162:165], v[134:137], v[48:63]
	v_mfma_f32_32x32x16_bf16 v[48:63], v[166:169], v[68:71], v[48:63]
	s_cbranch_scc1 .LBB0_265
	s_branch .LBB0_247

; #define DMAWAIT() asm volatile("s_waitcnt vmcnt(0)" ::: "memory")
; #define SMX_FIN(pbuf) do { _Pragma("unroll") for (int r = 0; r < 16; ++r) l_reg += S[r]; \
;     PK4S(0, po0); PK4S(8, po1); \
;     *(bf16x8*)(pw + (pbuf) * 16384) = po0; *(bf16x8*)(pw + (pbuf) * 16384 + 16) = po1; } while (0)
; #define VRD(D0, X) do { X##0 = tr_read<v_rd_off(D0, 0, 0)>(vb); X##1 = tr_read<v_rd_off(D0, 0, 1)>(vb); X##2 = tr_read<v_rd_off(D0, 1, 0)>(vb); X##3 = tr_read<v_rd_off(D0, 1, 1)>(vb); \
;     X##4 = tr_read<v_rd_off(D0, 2, 0)>(vb); X##5 = tr_read<v_rd_off(D0, 2, 1)>(vb); X##6 = tr_read<v_rd_off(D0, 3, 0)>(vb); X##7 = tr_read<v_rd_off(D0, 3, 1)>(vb); } while (0)
; #define LWAIT() do { asm volatile("s_waitcnt lgkmcnt(0)" ::: "memory"); SBAR(); } while (0)
; #define VMMP(D0, X) do { if (!(PROBE & 8)) VMM(D0, X); } while (0)
; #define SMXP(c) do { if (!(PROBE & 2)) { if (more) SMX_CH(c); } } while (0)
; template <int PROBE, int MODE>
; DI void dattn_body(const u16* __restrict__ Qb, const u16* __restrict__ Kh, const u16* __restrict__ Vh, u16* __restrict__ Ob, const u16* __restrict__ O1, float lam, const float* __restrict__ subg, int seq, int q0, float kmax2, char* lds) {
;     ...
;     LWAIT(); VRD(1, vc); VMMP(0, va); SMXP(0);
;     LWAIT(); VRD(2, va); VMMP(1, vc); SMXP(1);
;     LWAIT(); VRD(3, vc); VMMP(2, va); SMXP(2);
;     LWAIT(); VMMP(3, vc); SMXP(3);
;     if (!(PROBE & 2)) { if (more) SMX_FIN((j + 1) & 1); }
;     DMAWAIT();
;     __syncthreads();
.Lfast1_k_done:
	s_waitcnt lgkmcnt(6)
	v_mfma_f32_32x32x16_bf16 v[0:15], v[114:117], v[234:237], v[0:15]
	ds_read_b64_tr_b16 v[138:139], v215 offset:0x200
	ds_read_b64_tr_b16 v[140:141], v215 offset:0xa00
	s_waitcnt lgkmcnt(6)
	v_mfma_f32_32x32x16_bf16 v[0:15], v[130:133], v[238:241], v[0:15]
	ds_read_b64_tr_b16 v[142:143], v215 offset:0x1200
	ds_read_b64_tr_b16 v[144:145], v215 offset:0x1a00
	s_nop 1
	v_fma_f32 v118, v64, s12, v160
	v_fma_f32 v119, v65, s12, v160
	v_fma_f32 v120, v66, s12, v160
	v_fma_f32 v121, v67, s12, v160
	s_waitcnt lgkmcnt(6)
	v_mfma_f32_32x32x16_bf16 v[0:15], v[162:165], v[242:245], v[0:15]
	ds_read_b64_tr_b16 v[134:135], v233 offset:0x2200
	ds_read_b64_tr_b16 v[136:137], v233 offset:0x2a00
	v_fma_f32 v122, v68, s12, v160
	v_fma_f32 v123, v69, s12, v160
	v_exp_f32_e32 v118, v118
	v_exp_f32_e32 v119, v119
	s_waitcnt lgkmcnt(6)
	v_mfma_f32_32x32x16_bf16 v[0:15], v[166:169], v[246:249], v[0:15]
	ds_read_b64_tr_b16 v[126:127], v233 offset:0x3200
	ds_read_b64_tr_b16 v[128:129], v233 offset:0x3a00
	v_fma_f32 v124, v70, s12, v160
	v_fma_f32 v125, v71, s12, v160
	v_exp_f32_e32 v120, v120
	v_exp_f32_e32 v121, v121
	s_waitcnt lgkmcnt(6)
	v_mfma_f32_32x32x16_bf16 v[16:31], v[114:117], v[138:141], v[16:31]
	ds_read_b64_tr_b16 v[146:147], v215 offset:0x400
	ds_read_b64_tr_b16 v[148:149], v215 offset:0xc00
	v_exp_f32_e32 v122, v122
	v_exp_f32_e32 v123, v123
	v_add_f32_e32 v208, v118, v208
	v_add_f32_e32 v208, v119, v208
	s_waitcnt lgkmcnt(6)
	v_mfma_f32_32x32x16_bf16 v[16:31], v[130:133], v[142:145], v[16:31]
	ds_read_b64_tr_b16 v[142:143], v215 offset:0x1400
	ds_read_b64_tr_b16 v[144:145], v215 offset:0x1c00
	v_exp_f32_e32 v124, v124
	v_exp_f32_e32 v125, v125
	v_add_f32_e32 v208, v120, v208
	v_add_f32_e32 v208, v121, v208
	v_fma_f32 v244, v72, s12, v160
	v_fma_f32 v245, v73, s12, v160
	s_waitcnt lgkmcnt(6)
	v_mfma_f32_32x32x16_bf16 v[16:31], v[162:165], v[134:137], v[16:31]
	ds_read_b64_tr_b16 v[138:139], v233 offset:0x2400
	ds_read_b64_tr_b16 v[140:141], v233 offset:0x2c00
	v_fma_f32 v246, v74, s12, v160
	v_fma_f32 v247, v75, s12, v160
	v_add_f32_e32 v208, v122, v208
	v_add_f32_e32 v208, v123, v208
	s_waitcnt lgkmcnt(6)
	v_mfma_f32_32x32x16_bf16 v[16:31], v[166:169], v[126:129], v[16:31]
	ds_read_b64_tr_b16 v[64:65], v233 offset:0x3400
	ds_read_b64_tr_b16 v[66:67], v233 offset:0x3c00
	v_fma_f32 v76, v76, s12, v160
	v_fma_f32 v77, v77, s12, v160
	v_fma_f32 v78, v78, s12, v160
	v_fma_f32 v79, v79, s12, v160
	s_waitcnt lgkmcnt(6)
	v_mfma_f32_32x32x16_bf16 v[32:47], v[114:117], v[146:149], v[32:47]
	v_exp_f32_e32 v244, v244
	v_exp_f32_e32 v245, v245
	v_add_f32_e32 v208, v124, v208
	v_add_f32_e32 v208, v125, v208
	s_waitcnt lgkmcnt(4)
	v_mfma_f32_32x32x16_bf16 v[32:47], v[130:133], v[142:145], v[32:47]
	ds_read_b64_tr_b16 v[142:143], v215 offset:0x600
	ds_read_b64_tr_b16 v[144:145], v215 offset:0xe00
	ds_read_b64_tr_b16 v[126:127], v215 offset:0x1600
	ds_read_b64_tr_b16 v[128:129], v215 offset:0x1e00
	v_exp_f32_e32 v246, v246
	v_exp_f32_e32 v247, v247
	s_waitcnt lgkmcnt(6)
	v_mfma_f32_32x32x16_bf16 v[32:47], v[162:165], v[138:141], v[32:47]
	ds_read_b64_tr_b16 v[134:135], v233 offset:0x2600
	ds_read_b64_tr_b16 v[136:137], v233 offset:0x2e00
	v_exp_f32_e32 v76, v76
	v_exp_f32_e32 v77, v77
	v_add_f32_e32 v208, v244, v208
	v_add_f32_e32 v208, v245, v208
	s_waitcnt lgkmcnt(6)
	v_mfma_f32_32x32x16_bf16 v[32:47], v[166:169], v[64:67], v[32:47]
	ds_read_b64_tr_b16 v[68:69], v233 offset:0x3600
	ds_read_b64_tr_b16 v[70:71], v233 offset:0x3e00
	v_exp_f32_e32 v78, v78
	v_exp_f32_e32 v79, v79
	v_add_f32_e32 v208, v246, v208
	v_add_f32_e32 v208, v247, v208
	s_waitcnt lgkmcnt(6)
	v_mfma_f32_32x32x16_bf16 v[48:63], v[114:117], v[142:145], v[48:63]
	v_add_u32_e32 v64, s1, v210
	v_add_f32_e32 v208, v76, v208
	v_add_f32_e32 v208, v77, v208
	v_cvt_pk_bf16_f32 v114, v118, v119
	v_cvt_pk_bf16_f32 v115, v120, v121
	v_cvt_pk_bf16_f32 v116, v122, v123
	v_cvt_pk_bf16_f32 v117, v124, v125
	s_waitcnt lgkmcnt(4)
	v_mfma_f32_32x32x16_bf16 v[48:63], v[130:133], v[126:129], v[48:63]
	v_add_f32_e32 v208, v78, v208
	v_add_f32_e32 v208, v79, v208
	v_permlane32_swap_b32_e32 v114, v116
	v_permlane32_swap_b32_e32 v115, v117
	v_cvt_pk_bf16_f32 v130, v244, v245
	v_cvt_pk_bf16_f32 v131, v246, v247
	v_cvt_pk_bf16_f32 v132, v76, v77
	v_cvt_pk_bf16_f32 v133, v78, v79
	ds_write_b128 v64, v[114:117]
	s_nop 0
	v_permlane32_swap_b32_e32 v130, v132
	v_permlane32_swap_b32_e32 v131, v133
	ds_write_b128 v64, v[130:133] offset:16
	s_add_i32 s40, s40, 1
	s_add_i32 s0, s0, 64
	s_add_i32 s25, s25, 0x8000
	s_cmp_eq_u32 s83, s40
	s_waitcnt vmcnt(0) lgkmcnt(0)
	s_barrier
	v_mfma_f32_32x32x16_bf16 v[48:63], v[162:165], v[134:137], v[48:63]
	v_mfma_f32_32x32x16_bf16 v[48:63], v[166:169], v[68:71], v[48:63]
	s_cbranch_scc1 .LBB0_303
	s_branch .LBB0_285
